# P0 static deal rebalanced: the remainder trips of the x-row and cache conversion loops rotated onto the waves that have one transpose item fewer
# speedup vs baseline: 1.0044x; 1.0044x over previous
.LBB0_122:
	s_cmpk_gt_i32 s30, 0x207f
	v_lshlrev_b32_e32 v32, 3, v36
	v_cmp_eq_u32_e32 vcc, 0, v36
	s_cbranch_scc1 .LBB0_129
	v_mbcnt_lo_u32_b32 v2, -1, 0
	v_mbcnt_hi_u32_b32 v2, -1, v2
	v_and_b32_e32 v3, 64, v2
	v_add_u32_e32 v3, 64, v3
	v_xor_b32_e32 v4, 1, v2
	v_cmp_lt_i32_e64 s[4:5], v4, v3
	v_xor_b32_e32 v5, 2, v2
	v_xor_b32_e32 v6, 4, v2
	v_cndmask_b32_e64 v4, v2, v4, s[4:5]
	v_cmp_lt_i32_e64 s[4:5], v5, v3
	v_xor_b32_e32 v7, 8, v2
	s_load_dwordx4 s[8:11], s[0:1], 0x0
	v_cndmask_b32_e64 v5, v2, v5, s[4:5]
	v_cmp_lt_i32_e64 s[4:5], v6, v3
	v_xor_b32_e32 v8, 16, v2
	s_add_i32 s98, s30, 0x1e0
	s_and_b32 s98, s98, 0x7ff
	s_cmp_eq_u32 s3, 0x100
	s_cselect_b32 s98, s98, s30
	s_lshl_b32 s6, s98, 1
	v_cndmask_b32_e64 v6, v2, v6, s[4:5]
	v_cmp_lt_i32_e64 s[4:5], v7, v3
	v_xor_b32_e32 v9, 32, v2
	s_ashr_i32 s7, s6, 31
	v_cndmask_b32_e64 v7, v2, v7, s[4:5]
	v_cmp_lt_i32_e64 s[4:5], v8, v3
	s_ashr_i32 s35, s34, 31
	s_lshl_b64 s[14:15], s[34:35], 11
	v_cndmask_b32_e64 v8, v2, v8, s[4:5]
	v_cmp_lt_i32_e64 s[4:5], v9, v3
	s_lshl_b64 s[16:17], s[6:7], 3
	s_lshl_b64 s[18:19], s[34:35], 3
	v_cndmask_b32_e64 v2, v2, v9, s[4:5]
	s_lshl_b64 s[4:5], s[6:7], 11
	v_lshlrev_b32_e32 v9, 2, v2
	v_lshl_or_b32 v2, v36, 3, s4
	v_mov_b32_e32 v3, s5
	s_lshl_b64 s[4:5], s[6:7], 12
	s_waitcnt lgkmcnt(0)
	s_add_u32 s4, s8, s4
	s_addc_u32 s5, s9, s5
	v_mov_b32_e32 v33, 0
	s_add_u32 s20, s4, 0x1000
	v_lshl_add_u64 v[0:1], s[64:65], 0, v[32:33]
	s_mov_b32 s13, 0
	v_lshlrev_b32_e32 v4, 2, v4
	v_lshlrev_b32_e32 v5, 2, v5
	v_lshlrev_b32_e32 v6, 2, v6
	v_lshlrev_b32_e32 v7, 2, v7
	v_lshlrev_b32_e32 v8, 2, v8
	s_addc_u32 s21, s5, 0
	s_lshl_b64 s[22:23], s[34:35], 12
	v_lshlrev_b32_e32 v10, 4, v36
	s_mov_b32 s26, 0x3000000
	s_mov_b32 s27, 0x49800000
	s_branch .LBB0_125

.LBB0_137:
	s_or_b64 exec, exec, s[4:5]
	s_cmpk_gt_i32 s30, 0x283f
	s_cbranch_scc1 .LBB0_177
	s_add_u32 s22, s52, 0x1080000
	s_addc_u32 s23, s53, 0
	s_lshl_b32 s24, s3, 5
	s_add_i32 s98, s30, 0x160
	s_and_b32 s98, s98, 0x7ff
	s_cmp_eq_u32 s3, 0x100
	s_cselect_b32 s98, s98, s30
	s_lshl_b32 s25, s98, 2
	s_mov_b32 s26, 0x2100000
	v_lshlrev_b32_e32 v33, 2, v32
	s_branch .LBB0_142
